# SGU items: second batch of gate-parameter loads issued with the first batch into free registers (one round trip per item)
# speedup vs baseline: 1.0038x; 1.0038x over previous
; DI void sgu_item(int g, int bc, int par, const bf16_t* SGW, const bf16_t* Vg, const float* VST, const float* lng, const float* lnb, const float* sgb, bf16_t* U, LAS unsigned char* lds) {
;     ...
;     u32x4 wreg[4];
; #pragma unroll
;     for (int i = 0; i < 4; ++i) { const int c = tid + i * 512, rr = c >> 4, cc = c & 15; wreg[i] = *(const u32x4*)(SGW + (size_t)g * 16384 + rr * 128 + cc * 8); }
;     const int s = tid & 127, dg = tid >> 7, row = row0 + s;
;     f32x4 pst[8];
; #pragma unroll
;     for (int i = 0; i < 8; ++i) pst[i] = *(const f32x4*)(VST + (size_t)row * 32 + 4 * i);
;     const u32x4 a = *(const u32x4*)(Vg + (size_t)row * 512 + g * 64 + dg * 16), b = *(const u32x4*)(Vg + (size_t)row * 512 + g * 64 + dg * 16 + 8);
;     bf16_t* up = U + (size_t)(row0 + t) * 512 + g * 64 + 4 * q;
;     u32x2 uu[4];
; #pragma unroll
;     for (int db = 0; db < 4; ++db) uu[db] = *(const u32x2*)(up + 16 * db);
;     const float bias = sgb[g * 128 + t];
.LBB0_1303:
	s_ashr_i32 s14, s12, 7
	s_ashr_i32 s15, s14, 31
	s_lshl_b64 s[16:17], s[14:15], 15
	s_lshl_b32 s13, s12, 7
	v_lshl_add_u64 v[32:33], v[20:21], 0, s[16:17]
	s_and_b32 s17, s13, 0x3f80
	v_lshl_add_u64 v[34:35], v[32:33], 0, v[22:23]
	v_lshl_add_u64 v[4:5], v[32:33], 0, v[24:25]
	v_or_b32_e32 v38, s17, v42
	flat_load_dwordx4 v[0:3], v[34:35]
	s_nop 0
	flat_load_dwordx4 v[4:7], v[4:5]
	v_lshlrev_b32_e32 v16, 7, v38
	v_lshl_add_u64 v[36:37], s[4:5], 0, v[16:17]
	flat_load_dwordx4 v[8:11], v[36:37]
	flat_load_dwordx4 v[12:15], v[36:37] offset:16
	flat_load_dwordx4 v[56:59], v[36:37] offset:32
	flat_load_dwordx4 v[60:63], v[36:37] offset:48
	v_add_co_u32_e32 v34, vcc, s7, v34
	s_lshl_b32 s14, s14, 6
	s_nop 0
	v_addc_co_u32_e32 v35, vcc, 0, v35, vcc
	flat_load_dwordx4 v[64:67], v[34:35]
	flat_load_dwordx4 v[68:71], v[36:37] offset:64
	flat_load_dwordx4 v[72:75], v[36:37] offset:80
	flat_load_dwordx4 v[76:79], v[36:37] offset:96
	flat_load_dwordx4 v[80:83], v[36:37] offset:112
	s_ashr_i32 s15, s14, 31
	v_lshl_add_u64 v[32:33], v[32:33], 0, v[26:27]
	v_lshlrev_b32_e32 v16, 10, v38
	s_lshl_b64 s[18:19], s[14:15], 1
	flat_load_dwordx4 v[84:87], v[32:33]
	v_lshl_add_u64 v[36:37], s[2:3], 0, v[16:17]
	v_lshl_add_u64 v[36:37], v[36:37], 0, s[18:19]
	v_lshl_add_u64 v[32:33], v[36:37], 0, v[28:29]
	flat_load_dwordx4 v[88:91], v[32:33]
	v_add_u32_e32 v34, s14, v131
	v_ashrrev_i32_e32 v35, 31, v34
	v_readlane_b32 s36, v249, 33
	v_lshlrev_b64 v[34:35], 2, v[34:35]
	v_readlane_b32 s40, v249, 37
	v_readlane_b32 s41, v249, 38
	v_readlane_b32 s38, v249, 35
	v_readlane_b32 s39, v249, 36
	v_lshl_add_u64 v[114:115], s[40:41], 0, v[34:35]
	v_readfirstlane_b32 s14, v196
	v_lshl_add_u64 v[112:113], s[38:39], 0, v[34:35]
	global_load_dwordx4 v[92:95], v[114:115], off
	global_load_dwordx4 v[96:99], v[112:113], off
	global_load_dwordx4 v[100:103], v[112:113], off offset:16
	global_load_dwordx4 v[104:107], v[114:115], off offset:16
	global_load_dwordx4 v[200:203], v[112:113], off offset:48
	global_load_dwordx4 v[204:207], v[112:113], off offset:32
	global_load_dwordx4 v[208:211], v[114:115], off offset:48
	global_load_dwordx4 v[212:215], v[114:115], off offset:32
	s_mul_i32 s13, s6, 0xcc00
	s_lshr_b32 s21, s14, 2
	s_add_i32 s16, s13, 0
	s_and_b32 s21, s21, 0x3ffffff0
	s_and_b32 s20, s12, 0xffffff80
	v_add_u32_e32 v16, s16, v18
	v_or_b32_e32 v35, s21, v129
	v_add_u32_e32 v116, v16, v43
	v_add_u32_e32 v117, v16, v44
	v_add_u32_e32 v118, v16, v45
	v_add_u32_e32 v34, s20, v35
	v_add_u32_e32 v16, s17, v35
	v_readlane_b32 s44, v249, 41
	v_readlane_b32 s45, v249, 42
	v_ashrrev_i32_e32 v35, 31, v34
	v_lshlrev_b64 v[36:37], 10, v[16:17]
	v_lshl_add_u64 v[34:35], v[34:35], 2, s[44:45]
	v_lshl_add_u64 v[36:37], s[8:9], 0, v[36:37]
	global_load_dword v16, v[34:35], off
	flat_load_dwordx4 v[108:111], v[32:33] offset:16
	v_lshl_add_u64 v[32:33], v[36:37], 0, s[18:19]
	v_lshl_add_u64 v[32:33], v[32:33], 0, v[30:31]
	flat_load_dwordx2 v[40:41], v[32:33]
	flat_load_dwordx2 v[38:39], v[32:33] offset:32
	flat_load_dwordx2 v[36:37], v[32:33] offset:64
	flat_load_dwordx2 v[34:35], v[32:33] offset:96
	s_lshr_b32 s15, s14, 7
	s_lshr_b32 s14, s14, 6
	s_mulk_i32 s14, 0x1100
	s_add_i32 s15, s15, 1
	v_readlane_b32 s37, v249, 34
	v_readlane_b32 s42, v249, 39
	v_readlane_b32 s43, v249, 40
	v_readlane_b32 s46, v249, 43
	v_readlane_b32 s47, v249, 44
	v_readlane_b32 s48, v249, 45
	v_readlane_b32 s49, v249, 46
	v_readlane_b32 s50, v249, 47
	v_readlane_b32 s51, v249, 48
	s_waitcnt vmcnt(0) lgkmcnt(0)
; #define LAS __attribute__((address_space(3)))
; DI unsigned f2bf(float f) { unsigned u = __builtin_bit_cast(unsigned, f); return (u + 0x7fffu + ((u >> 16) & 1u)) >> 16; }
; DI float bflo(unsigned w) { return __uint_as_float(w << 16); }
; DI float bfhi(unsigned w) { return __uint_as_float(w & 0xffff0000u); }
; DI void sgu_item(int g, int bc, int par, const bf16_t* SGW, const bf16_t* Vg, const float* VST, const float* lng, const float* lnb, const float* sgb, bf16_t* U, LAS unsigned char* lds) {
;     ...
;     for (int i = 0; i < 4; ++i) { const int c = tid + i * 512, rr = c >> 4, cc = c & 15; *(LAS u32x4*)(Wl + rr * RS + cc * 16) = wreg[i]; }
;     {
;         float s1 = 0.f, s2 = 0.f;
; #pragma unroll
;         for (int i = 0; i < 8; ++i) { s1 += pst[i][0] + pst[i][2]; s2 += pst[i][1] + pst[i][3]; }
;         const float mu = s1 * (1.0f / 512.0f), var = s2 * (1.0f / 512.0f) - mu * mu, rstd = __builtin_amdgcn_rsqf(fmaxf(var, 0.f) + EPS);
;         const unsigned wd[8] = {a.x, a.y, a.z, a.w, b.x, b.y, b.z, b.w};
; #pragma unroll
;         for (int i = 0; i < 8; ++i) {
;             const int d = dg * 16 + 2 * i, c = g * 64 + d;
;             const float v0 = (bflo(wd[i]) - mu) * rstd * lng[c] + lnb[c], v1 = (bfhi(wd[i]) - mu) * rstd * lng[c + 1] + lnb[c + 1];
;             *(LAS bf16_t*)(Vl + d * RS + s * 2) = (bf16_t)f2bf(v0); *(LAS bf16_t*)(Vl + (d + 1) * RS + s * 2) = (bf16_t)f2bf(v1);
;         }
;     }
;     __syncthreads();
;     f32x4 acc[4];
; #pragma unroll
;     for (int db = 0; db < 4; ++db) acc[db] = (f32x4){0.f, 0.f, 0.f, 0.f};
	ds_write_b128 v116, v[0:3]
	ds_write_b128 v117, v[4:7]
	v_add_f32_e32 v0, v8, v10
	v_add_f32_e32 v1, v9, v11
	v_add_f32_e32 v2, v12, v14
	v_add_f32_e32 v0, 0, v0
	v_add_f32_e32 v3, v13, v15
	v_add_f32_e32 v4, v56, v58
	v_add_f32_e32 v1, 0, v1
	v_add_f32_e32 v0, v0, v2
	v_add_f32_e32 v5, v57, v59
	v_add_f32_e32 v6, v60, v62
	v_add_f32_e32 v1, v1, v3
	v_add_f32_e32 v0, v0, v4
	v_add_f32_e32 v7, v61, v63
	v_add_f32_e32 v1, v1, v5
	v_add_f32_e32 v0, v0, v6
	v_add_f32_e32 v2, v68, v70
	v_add_f32_e32 v1, v1, v7
	v_add_f32_e32 v0, v0, v2
	v_add_f32_e32 v2, v69, v71
	ds_write_b128 v116, v[64:67] offset:17408
	v_add_f32_e32 v56, v1, v2
	v_add_f32_e32 v1, v72, v74
	v_add_f32_e32 v57, v0, v1
	v_add_f32_e32 v58, v73, v75
	v_add_f32_e32 v56, v56, v58
	v_add_f32_e32 v58, v76, v78
	v_add_f32_e32 v57, v57, v58
	v_add_f32_e32 v58, v77, v79
	v_add_f32_e32 v56, v56, v58
	v_add_f32_e32 v58, v80, v82
	v_add_f32_e32 v57, v57, v58
	v_add_f32_e32 v58, v81, v83
	v_add_f32_e32 v56, v56, v58
	v_mul_f32_e32 v58, 0x3b000000, v57
	v_mul_f32_e32 v58, v58, v58
	v_fma_f32 v56, v56, s10, -v58
	v_max_f32_e32 v56, 0, v56
	v_add_f32_e32 v56, 0x358637bd, v56
	v_rsq_f32_e32 v56, v56
	v_lshlrev_b32_e32 v58, 16, v88
	v_fmac_f32_e32 v58, 0xbb000000, v57
	v_and_b32_e32 v59, 0xffff0000, v88
	v_mul_f32_e32 v58, v58, v56
	v_fma_f32 v58, v58, v96, v92
	v_fmac_f32_e32 v59, 0xbb000000, v57
	v_mul_f32_e32 v59, v59, v56
	v_bfe_u32 v60, v58, 16, 1
	v_fma_f32 v59, v59, v97, v93
	v_add3_u32 v58, v58, v60, s11
	v_add3_u32 v60, s16, v47, v46
	ds_write_b128 v118, v[84:87]
	ds_write_b16_d16_hi v60, v58 offset:34816
	v_bfe_u32 v58, v59, 16, 1
	v_add3_u32 v58, v59, v58, s11
	ds_write_b16_d16_hi v60, v58 offset:35088
	v_lshlrev_b32_e32 v58, 16, v89
	v_fmac_f32_e32 v58, 0xbb000000, v57
	v_and_b32_e32 v59, 0xffff0000, v89
	v_mul_f32_e32 v58, v58, v56
	v_fmac_f32_e32 v59, 0xbb000000, v57
	v_fma_f32 v58, v58, v98, v94
	v_mul_f32_e32 v59, v59, v56
	v_fmac_f32_e32 v95, v59, v99
	v_bfe_u32 v59, v58, 16, 1
	v_add3_u32 v58, v58, v59, s11
	v_add3_u32 v59, s16, v48, v46
	ds_write_b16_d16_hi v59, v58 offset:34816
	v_bfe_u32 v58, v95, 16, 1
	v_add3_u32 v58, v95, v58, s11
	ds_write_b16_d16_hi v59, v58 offset:35088
	v_lshlrev_b32_e32 v58, 16, v90
	v_fmac_f32_e32 v58, 0xbb000000, v57
	v_mul_f32_e32 v58, v58, v56
	v_and_b32_e32 v59, 0xffff0000, v90
	v_fma_f32 v58, v58, v100, v104
	v_fmac_f32_e32 v59, 0xbb000000, v57
	v_mul_f32_e32 v59, v59, v56
	v_bfe_u32 v60, v58, 16, 1
	v_fma_f32 v59, v59, v101, v105
	v_add3_u32 v58, v58, v60, s11
	v_add3_u32 v60, s16, v49, v46
	ds_write_b16_d16_hi v60, v58 offset:34816
	v_bfe_u32 v58, v59, 16, 1
	v_add3_u32 v58, v59, v58, s11
	ds_write_b16_d16_hi v60, v58 offset:35088
	v_lshlrev_b32_e32 v58, 16, v91
	v_fmac_f32_e32 v58, 0xbb000000, v57
	v_and_b32_e32 v59, 0xffff0000, v91
	v_mul_f32_e32 v58, v58, v56
	v_fmac_f32_e32 v59, 0xbb000000, v57
	v_fma_f32 v58, v58, v102, v106
	v_mul_f32_e32 v59, v59, v56
	v_fmac_f32_e32 v107, v59, v103
	v_bfe_u32 v59, v58, 16, 1
	v_add3_u32 v58, v58, v59, s11
	v_add3_u32 v59, s16, v50, v46
	ds_write_b16_d16_hi v59, v58 offset:34816
	v_bfe_u32 v58, v107, 16, 1
	v_add3_u32 v58, v107, v58, s11
	ds_write_b16_d16_hi v59, v58 offset:35088
	v_lshlrev_b32_e32 v58, 16, v108
	v_fmac_f32_e32 v58, 0xbb000000, v57
	v_mul_f32_e32 v58, v58, v56
	s_waitcnt vmcnt(0)
	v_fma_f32 v204, v58, v204, v212
	v_and_b32_e32 v12, 0xffff0000, v108
	v_fmac_f32_e32 v12, 0xbb000000, v57
	v_mul_f32_e32 v12, v12, v56
	v_fma_f32 v205, v12, v205, v213
	v_bfe_u32 v12, v204, 16, 1
	v_add3_u32 v204, v204, v12, s11
	v_add3_u32 v12, s16, v51, v46
	ds_write_b16_d16_hi v12, v204 offset:34816
	v_bfe_u32 v4, v205, 16, 1
	v_add3_u32 v4, v205, v4, s11
	ds_write_b16_d16_hi v12, v4 offset:35088
	v_lshlrev_b32_e32 v4, 16, v109
	v_fmac_f32_e32 v4, 0xbb000000, v57
	v_and_b32_e32 v5, 0xffff0000, v109
	v_mul_f32_e32 v4, v4, v56
	v_fmac_f32_e32 v5, 0xbb000000, v57
	v_fma_f32 v4, v4, v206, v214
	v_mul_f32_e32 v5, v5, v56
	v_fmac_f32_e32 v215, v5, v207
	v_bfe_u32 v5, v4, 16, 1
	v_add3_u32 v4, v4, v5, s11
	v_add3_u32 v5, s16, v52, v46
	ds_write_b16_d16_hi v5, v4 offset:34816
	v_bfe_u32 v4, v215, 16, 1
	v_add3_u32 v4, v215, v4, s11
	ds_write_b16_d16_hi v5, v4 offset:35088
	v_lshlrev_b32_e32 v4, 16, v110
	v_fmac_f32_e32 v4, 0xbb000000, v57
	v_mul_f32_e32 v4, v4, v56
	v_fma_f32 v200, v4, v200, v208
	v_and_b32_e32 v4, 0xffff0000, v110
	v_fmac_f32_e32 v4, 0xbb000000, v57
	v_mul_f32_e32 v4, v4, v56
	v_fma_f32 v201, v4, v201, v209
	v_bfe_u32 v4, v200, 16, 1
	v_add3_u32 v200, v200, v4, s11
	v_add3_u32 v4, s16, v53, v46
	ds_write_b16_d16_hi v4, v200 offset:34816
	v_bfe_u32 v0, v201, 16, 1
	v_add3_u32 v0, v201, v0, s11
	ds_write_b16_d16_hi v4, v0 offset:35088
	v_lshlrev_b32_e32 v0, 16, v111
	v_fmac_f32_e32 v0, 0xbb000000, v57
	v_and_b32_e32 v1, 0xffff0000, v111
	v_mul_f32_e32 v0, v0, v56
	v_fmac_f32_e32 v1, 0xbb000000, v57
	v_fma_f32 v0, v0, v202, v210
	v_mul_f32_e32 v1, v1, v56
	v_fmac_f32_e32 v211, v1, v203
	v_bfe_u32 v1, v0, 16, 1
	v_add3_u32 v0, v0, v1, s11
	v_add3_u32 v1, s16, v54, v46
	ds_write_b16_d16_hi v1, v0 offset:34816
	v_bfe_u32 v0, v211, 16, 1
	v_add3_u32 v0, v211, v0, s11
	v_add_u32_e32 v56, s13, v55
	s_add_i32 s13, s13, s14
	ds_write_b16_d16_hi v1, v0 offset:35088
	v_add_u32_e32 v57, s13, v19
	v_mov_b32_e32 v0, 0
	v_mov_b32_e32 v1, v17
	v_mov_b32_e32 v2, v17
	v_mov_b32_e32 v3, v17
	v_mov_b32_e32 v12, 0
	v_mov_b32_e32 v13, v17
	v_mov_b32_e32 v14, v17
	v_mov_b32_e32 v15, v17
	v_mov_b32_e32 v8, 0
	v_mov_b32_e32 v9, v17
	v_mov_b32_e32 v10, v17
	v_mov_b32_e32 v11, v17
	v_mov_b32_e32 v4, 0
	v_mov_b32_e32 v5, v17
	v_mov_b32_e32 v6, v17
	v_mov_b32_e32 v7, v17
	s_waitcnt lgkmcnt(0)
	s_barrier
